# P5 rms phase rewritten by hand: all row loads up front, 4 rows per reduction batch, leftover-row partial slices loaded together
# speedup vs baseline: 1.0451x; 1.0006x over previous
; template <int NSLICE> __device__ __forceinline__ void rms_phase(ArgP a, const float* g, bool final_out, int G) {
;     int tid_ = threadIdx.x; asm volatile("" : "+v"(tid_));
;     const int tid = tid_, lane = tid & 63, wave = tid >> 6;
;     const int gw = blockIdx.x * NWAVES + wave, NGW = G * NWAVES;
;     bf16* H = (bf16*)(a->ws + WS_H); bf16* XN = (bf16*)(a->ws + WS_XN);
;     for (int m = gw; m < R_META; m += 2 * NGW) {
;         const int m2 = m + NGW; const bool has2 = m2 < R_META;
;         f32x4 v[4], u[4];
;         load_bf16_row(H + (size_t)m * DM, lane, v); load_bf16_row(H + (size_t)(has2 ? m2 : m) * DM, lane, u);
;         float rs; f32x4 y[4];
;         rms_row(v, g, lane, rs, y);
;         if (!final_out) store_bf16_row(XN + (size_t)m * DM, lane, y);
;         else { float* o = a->out + O_YP + (size_t)m * DM;
; #pragma unroll
;             for (int j = 0; j < 4; ++j) *((f32x4*)o + lane + 64 * j) = y[j]; }
;         if (has2) {
;             rms_row(u, g, lane, rs, y);
;             if (!final_out) store_bf16_row(XN + (size_t)m2 * DM, lane, y);
;             else { float* o = a->out + O_YP + (size_t)m2 * DM;
; #pragma unroll
;                 for (int j = 0; j < 4; ++j) *((f32x4*)o + lane + 64 * j) = y[j]; }
;         }
;     }
;     for (int t = (NGW - 1 - gw); t < M_REAL - R_META; t += NGW) {
;         const int m = R_META + t;
;         if (final_out && m < R_SAMP) continue;
;         f32x4 v[4]; load_bf16_row(H + (size_t)m * DM, lane, v);
;         const bf16* PART = (const bf16*)(a->ws + WS_P + 6 * ROWBUF) + (size_t)t * DM;
; #pragma unroll
;         for (int sl = 0; sl < NSLICE; ++sl) {
;             f32x4 pv[4]; load_bf16_row(PART + (size_t)sl * (MP - R_META) * DM, lane, pv);
; #pragma unroll
;             for (int j = 0; j < 4; ++j) v[j] = v[j] + pv[j];
;         }
;         if (!final_out) store_bf16_row(H + (size_t)m * DM, lane, v);
;         float rs; f32x4 y[4]; rms_row(v, g, lane, rs, y);
;         if (!final_out) store_bf16_row(XN + (size_t)m * DM, lane, y);
;         else { float* o = a->out + O_YS + (size_t)(m - R_SAMP) * DM;
; #pragma unroll
;             for (int j = 0; j < 4; ++j) *((f32x4*)o + lane + 64 * j) = y[j]; }
;     }
; }
.LBB0_1053:
	s_or_b64 exec, exec, s[34:35]
	v_readlane_b32 s2, v254, 4
	v_readlane_b32 s3, v254, 5
	s_mov_b64 s[0:1], s[2:3]
	s_waitcnt lgkmcnt(0)
	s_barrier
	v_readlane_b32 s0, v254, 4
	v_readlane_b32 s1, v254, 5
	s_nop 1
	s_load_dwordx2 s[2:3], s[0:1], 0x80
	s_load_dwordx2 s[6:7], s[0:1], 0x58
	v_readlane_b32 s8, v255, 6
	s_nop 1
	s_lshl_b32 s8, s8, 12
	v_lshrrev_b32_e32 v183, 6, v193
	v_and_b32_e32 v182, 63, v193
	v_readlane_b32 s10, v254, 9
	v_readfirstlane_b32 s9, v183
	s_nop 1
	s_add_u32 s9, s9, s10
	s_sub_u32 s10, 0x7ff, s9
	s_lshl_b32 s11, s9, 11
	v_lshlrev_b32_e32 v183, 4, v182
	v_add_u32_e32 v184, s11, v183
	s_lshl_b32 s11, s10, 11
	v_add_u32_e32 v185, s11, v183
	v_lshlrev_b32_e32 v186, 5, v182
	v_xor_b32_e32 v176, 1, v182
	v_lshlrev_b32_e32 v176, 2, v176
	v_xor_b32_e32 v177, 2, v182
	v_lshlrev_b32_e32 v177, 2, v177
	v_xor_b32_e32 v178, 4, v182
	v_lshlrev_b32_e32 v178, 2, v178
	v_xor_b32_e32 v179, 8, v182
	v_lshlrev_b32_e32 v179, 2, v179
	v_xor_b32_e32 v180, 16, v182
	v_lshlrev_b32_e32 v180, 2, v180
	v_xor_b32_e32 v181, 32, v182
	v_lshlrev_b32_e32 v181, 2, v181
	s_waitcnt lgkmcnt(0)
	s_add_u32 s6, s6, s8
	s_addc_u32 s7, s7, 0
	s_cmp_lt_u32 s10, 0x480
	s_cbranch_scc0 .Lrms5_noleft_ld
	s_add_u32 s12, s2, 0x9580000
	s_addc_u32 s13, s3, 0
	global_load_dwordx4 v[80:83], v185, s[12:13]
	global_load_dwordx4 v[84:87], v185, s[12:13] offset:1024
	s_add_u32 s12, s2, 0x18980000
	s_addc_u32 s13, s3, 0
	global_load_dwordx4 v[88:91], v185, s[12:13]
	global_load_dwordx4 v[92:95], v185, s[12:13] offset:1024
	s_add_u32 s12, s2, 0x18c00000
	s_addc_u32 s13, s3, 0
	global_load_dwordx4 v[96:99], v185, s[12:13]
	global_load_dwordx4 v[100:103], v185, s[12:13] offset:1024
	s_add_u32 s12, s2, 0x18e80000
	s_addc_u32 s13, s3, 0
	global_load_dwordx4 v[104:107], v185, s[12:13]
	global_load_dwordx4 v[108:111], v185, s[12:13] offset:1024
	s_add_u32 s12, s2, 0x19100000
	s_addc_u32 s13, s3, 0
	global_load_dwordx4 v[112:115], v185, s[12:13]
	global_load_dwordx4 v[116:119], v185, s[12:13] offset:1024
.Lrms5_noleft_ld:
	global_load_dwordx4 v[0:3], v186, s[6:7]
	global_load_dwordx4 v[4:7], v186, s[6:7] offset:16
	global_load_dwordx4 v[8:11], v186, s[6:7] offset:2048
	global_load_dwordx4 v[12:15], v186, s[6:7] offset:2064
	s_add_u32 s12, s2, 0x7580000
	s_addc_u32 s13, s3, 0
	global_load_dwordx4 v[16:19], v184, s[12:13]
	global_load_dwordx4 v[20:23], v184, s[12:13] offset:1024
	s_add_u32 s12, s2, 0x7980000
	s_addc_u32 s13, s3, 0
	global_load_dwordx4 v[24:27], v184, s[12:13]
	global_load_dwordx4 v[28:31], v184, s[12:13] offset:1024
	s_add_u32 s12, s2, 0x7d80000
	s_addc_u32 s13, s3, 0
	global_load_dwordx4 v[32:35], v184, s[12:13]
	global_load_dwordx4 v[36:39], v184, s[12:13] offset:1024
	s_add_u32 s12, s2, 0x8180000
	s_addc_u32 s13, s3, 0
	global_load_dwordx4 v[40:43], v184, s[12:13]
	global_load_dwordx4 v[44:47], v184, s[12:13] offset:1024
	s_add_u32 s12, s2, 0x8580000
	s_addc_u32 s13, s3, 0
	global_load_dwordx4 v[48:51], v184, s[12:13]
	global_load_dwordx4 v[52:55], v184, s[12:13] offset:1024
	s_add_u32 s12, s2, 0x8980000
	s_addc_u32 s13, s3, 0
	global_load_dwordx4 v[56:59], v184, s[12:13]
	global_load_dwordx4 v[60:63], v184, s[12:13] offset:1024
	s_add_u32 s12, s2, 0x8d80000
	s_addc_u32 s13, s3, 0
	global_load_dwordx4 v[64:67], v184, s[12:13]
	global_load_dwordx4 v[68:71], v184, s[12:13] offset:1024
	s_add_u32 s12, s2, 0x9180000
	s_addc_u32 s13, s3, 0
	global_load_dwordx4 v[72:75], v184, s[12:13]
	global_load_dwordx4 v[76:79], v184, s[12:13] offset:1024
	s_waitcnt vmcnt(8)
	v_lshlrev_b32_e32 v210, 16, v16
	v_and_b32_e32 v211, 0xffff0000, v16
	v_mul_f32_e32 v212, v210, v210
	v_mul_f32_e32 v213, v211, v211
	v_lshlrev_b32_e32 v214, 16, v24
	v_and_b32_e32 v215, 0xffff0000, v24
	v_mul_f32_e32 v216, v214, v214
	v_mul_f32_e32 v217, v215, v215
	v_lshlrev_b32_e32 v218, 16, v32
	v_and_b32_e32 v219, 0xffff0000, v32
	v_mul_f32_e32 v220, v218, v218
	v_mul_f32_e32 v221, v219, v219
	v_lshlrev_b32_e32 v222, 16, v40
	v_and_b32_e32 v223, 0xffff0000, v40
	v_mul_f32_e32 v224, v222, v222
	v_mul_f32_e32 v225, v223, v223
	v_lshlrev_b32_e32 v210, 16, v17
	v_and_b32_e32 v211, 0xffff0000, v17
	v_fmac_f32_e32 v212, v210, v210
	v_fmac_f32_e32 v213, v211, v211
	v_lshlrev_b32_e32 v214, 16, v25
	v_and_b32_e32 v215, 0xffff0000, v25
	v_fmac_f32_e32 v216, v214, v214
	v_fmac_f32_e32 v217, v215, v215
	v_lshlrev_b32_e32 v218, 16, v33
	v_and_b32_e32 v219, 0xffff0000, v33
	v_fmac_f32_e32 v220, v218, v218
	v_fmac_f32_e32 v221, v219, v219
	v_lshlrev_b32_e32 v222, 16, v41
	v_and_b32_e32 v223, 0xffff0000, v41
	v_fmac_f32_e32 v224, v222, v222
	v_fmac_f32_e32 v225, v223, v223
	v_lshlrev_b32_e32 v210, 16, v18
	v_and_b32_e32 v211, 0xffff0000, v18
	v_fmac_f32_e32 v212, v210, v210
	v_fmac_f32_e32 v213, v211, v211
	v_lshlrev_b32_e32 v214, 16, v26
	v_and_b32_e32 v215, 0xffff0000, v26
	v_fmac_f32_e32 v216, v214, v214
	v_fmac_f32_e32 v217, v215, v215
	v_lshlrev_b32_e32 v218, 16, v34
	v_and_b32_e32 v219, 0xffff0000, v34
	v_fmac_f32_e32 v220, v218, v218
	v_fmac_f32_e32 v221, v219, v219
	v_lshlrev_b32_e32 v222, 16, v42
	v_and_b32_e32 v223, 0xffff0000, v42
	v_fmac_f32_e32 v224, v222, v222
	v_fmac_f32_e32 v225, v223, v223
	v_lshlrev_b32_e32 v210, 16, v19
	v_and_b32_e32 v211, 0xffff0000, v19
	v_fmac_f32_e32 v212, v210, v210
	v_fmac_f32_e32 v213, v211, v211
	v_lshlrev_b32_e32 v214, 16, v27
	v_and_b32_e32 v215, 0xffff0000, v27
	v_fmac_f32_e32 v216, v214, v214
	v_fmac_f32_e32 v217, v215, v215
	v_lshlrev_b32_e32 v218, 16, v35
	v_and_b32_e32 v219, 0xffff0000, v35
	v_fmac_f32_e32 v220, v218, v218
	v_fmac_f32_e32 v221, v219, v219
	v_lshlrev_b32_e32 v222, 16, v43
	v_and_b32_e32 v223, 0xffff0000, v43
	v_fmac_f32_e32 v224, v222, v222
; __device__ __forceinline__ float wave_sum(float v) {
; #pragma unroll
;     for (int o = 1; o < 64; o <<= 1) v += __shfl_xor(v, o);
;     return v;
; }
; __device__ __forceinline__ void rms_row(const f32x4 (&v)[4], const float* g, int lane, float& rs, f32x4 (&y)[4]) {
;     float s = 0.f;
; #pragma unroll
;     for (int j = 0; j < 4; ++j) s += (v[j].x * v[j].x + v[j].y * v[j].y) + (v[j].z * v[j].z + v[j].w * v[j].w);
;     rs = __builtin_amdgcn_rsqf(wave_sum(s) * (1.f / DM) + EPS);
; #pragma unroll
;     for (int j = 0; j < 4; ++j) { const f32x4 gv = *((const f32x4*)g + lane + 64 * j); y[j] = v[j] * rs * gv; }
; }
	v_fmac_f32_e32 v225, v223, v223
	v_lshlrev_b32_e32 v210, 16, v20
	v_and_b32_e32 v211, 0xffff0000, v20
	v_fmac_f32_e32 v212, v210, v210
	v_fmac_f32_e32 v213, v211, v211
	v_lshlrev_b32_e32 v214, 16, v28
	v_and_b32_e32 v215, 0xffff0000, v28
	v_fmac_f32_e32 v216, v214, v214
	v_fmac_f32_e32 v217, v215, v215
	v_lshlrev_b32_e32 v218, 16, v36
	v_and_b32_e32 v219, 0xffff0000, v36
	v_fmac_f32_e32 v220, v218, v218
	v_fmac_f32_e32 v221, v219, v219
	v_lshlrev_b32_e32 v222, 16, v44
	v_and_b32_e32 v223, 0xffff0000, v44
	v_fmac_f32_e32 v224, v222, v222
	v_fmac_f32_e32 v225, v223, v223
	v_lshlrev_b32_e32 v210, 16, v21
	v_and_b32_e32 v211, 0xffff0000, v21
	v_fmac_f32_e32 v212, v210, v210
	v_fmac_f32_e32 v213, v211, v211
	v_lshlrev_b32_e32 v214, 16, v29
	v_and_b32_e32 v215, 0xffff0000, v29
	v_fmac_f32_e32 v216, v214, v214
	v_fmac_f32_e32 v217, v215, v215
	v_lshlrev_b32_e32 v218, 16, v37
	v_and_b32_e32 v219, 0xffff0000, v37
	v_fmac_f32_e32 v220, v218, v218
	v_fmac_f32_e32 v221, v219, v219
	v_lshlrev_b32_e32 v222, 16, v45
	v_and_b32_e32 v223, 0xffff0000, v45
	v_fmac_f32_e32 v224, v222, v222
	v_fmac_f32_e32 v225, v223, v223
	v_lshlrev_b32_e32 v210, 16, v22
	v_and_b32_e32 v211, 0xffff0000, v22
	v_fmac_f32_e32 v212, v210, v210
	v_fmac_f32_e32 v213, v211, v211
	v_lshlrev_b32_e32 v214, 16, v30
	v_and_b32_e32 v215, 0xffff0000, v30
	v_fmac_f32_e32 v216, v214, v214
	v_fmac_f32_e32 v217, v215, v215
	v_lshlrev_b32_e32 v218, 16, v38
	v_and_b32_e32 v219, 0xffff0000, v38
	v_fmac_f32_e32 v220, v218, v218
	v_fmac_f32_e32 v221, v219, v219
	v_lshlrev_b32_e32 v222, 16, v46
	v_and_b32_e32 v223, 0xffff0000, v46
	v_fmac_f32_e32 v224, v222, v222
	v_fmac_f32_e32 v225, v223, v223
	v_lshlrev_b32_e32 v210, 16, v23
	v_and_b32_e32 v211, 0xffff0000, v23
	v_fmac_f32_e32 v212, v210, v210
	v_fmac_f32_e32 v213, v211, v211
	v_lshlrev_b32_e32 v214, 16, v31
	v_and_b32_e32 v215, 0xffff0000, v31
	v_fmac_f32_e32 v216, v214, v214
	v_fmac_f32_e32 v217, v215, v215
	v_lshlrev_b32_e32 v218, 16, v39
	v_and_b32_e32 v219, 0xffff0000, v39
	v_fmac_f32_e32 v220, v218, v218
	v_fmac_f32_e32 v221, v219, v219
	v_lshlrev_b32_e32 v222, 16, v47
	v_and_b32_e32 v223, 0xffff0000, v47
	v_fmac_f32_e32 v224, v222, v222
	v_fmac_f32_e32 v225, v223, v223
	v_add_f32_e32 v212, v212, v213
	v_add_f32_e32 v216, v216, v217
	v_add_f32_e32 v220, v220, v221
	v_add_f32_e32 v224, v224, v225
	ds_bpermute_b32 v210, v176, v212
	ds_bpermute_b32 v214, v176, v216
	ds_bpermute_b32 v218, v176, v220
	ds_bpermute_b32 v222, v176, v224
	s_waitcnt lgkmcnt(0)
	v_add_f32_e32 v212, v212, v210
	v_add_f32_e32 v216, v216, v214
	v_add_f32_e32 v220, v220, v218
	v_add_f32_e32 v224, v224, v222
	ds_bpermute_b32 v210, v177, v212
	ds_bpermute_b32 v214, v177, v216
	ds_bpermute_b32 v218, v177, v220
	ds_bpermute_b32 v222, v177, v224
	s_waitcnt lgkmcnt(0)
	v_add_f32_e32 v212, v212, v210
	v_add_f32_e32 v216, v216, v214
	v_add_f32_e32 v220, v220, v218
	v_add_f32_e32 v224, v224, v222
	ds_bpermute_b32 v210, v178, v212
	ds_bpermute_b32 v214, v178, v216
	ds_bpermute_b32 v218, v178, v220
	ds_bpermute_b32 v222, v178, v224
	s_waitcnt lgkmcnt(0)
	v_add_f32_e32 v212, v212, v210
	v_add_f32_e32 v216, v216, v214
	v_add_f32_e32 v220, v220, v218
	v_add_f32_e32 v224, v224, v222
	ds_bpermute_b32 v210, v179, v212
	ds_bpermute_b32 v214, v179, v216
	ds_bpermute_b32 v218, v179, v220
	ds_bpermute_b32 v222, v179, v224
	s_waitcnt lgkmcnt(0)
	v_add_f32_e32 v212, v212, v210
	v_add_f32_e32 v216, v216, v214
	v_add_f32_e32 v220, v220, v218
	v_add_f32_e32 v224, v224, v222
	ds_bpermute_b32 v210, v180, v212
	ds_bpermute_b32 v214, v180, v216
	ds_bpermute_b32 v218, v180, v220
	ds_bpermute_b32 v222, v180, v224
	s_waitcnt lgkmcnt(0)
	v_add_f32_e32 v212, v212, v210
	v_add_f32_e32 v216, v216, v214
	v_add_f32_e32 v220, v220, v218
	v_add_f32_e32 v224, v224, v222
	ds_bpermute_b32 v210, v181, v212
	ds_bpermute_b32 v214, v181, v216
	ds_bpermute_b32 v218, v181, v220
	ds_bpermute_b32 v222, v181, v224
	s_waitcnt lgkmcnt(0)
	v_add_f32_e32 v212, v212, v210
	v_add_f32_e32 v216, v216, v214
	v_add_f32_e32 v220, v220, v218
	v_add_f32_e32 v224, v224, v222
	v_fmamk_f32 v212, v212, 0x3a800000, v207
	v_fmamk_f32 v216, v216, 0x3a800000, v207
	v_fmamk_f32 v220, v220, 0x3a800000, v207
	v_fmamk_f32 v224, v224, 0x3a800000, v207
	v_rsq_f32_e32 v212, v212
	v_rsq_f32_e32 v216, v216
	v_rsq_f32_e32 v220, v220
	v_rsq_f32_e32 v224, v224
	s_nop 1
	v_lshlrev_b32_e32 v210, 16, v16
	v_and_b32_e32 v211, 0xffff0000, v16
	v_mul_f32_e32 v210, v210, v212
	v_mul_f32_e32 v211, v211, v212
	v_mul_f32_e32 v210, v210, v0
	v_mul_f32_e32 v211, v211, v1
	v_cvt_pk_bf16_f32 v16, v210, v211
	v_lshlrev_b32_e32 v210, 16, v17
	v_and_b32_e32 v211, 0xffff0000, v17
	v_mul_f32_e32 v210, v210, v212
	v_mul_f32_e32 v211, v211, v212
	v_mul_f32_e32 v210, v210, v2
	v_mul_f32_e32 v211, v211, v3
	v_cvt_pk_bf16_f32 v17, v210, v211
	v_lshlrev_b32_e32 v210, 16, v18
	v_and_b32_e32 v211, 0xffff0000, v18
	v_mul_f32_e32 v210, v210, v212
	v_mul_f32_e32 v211, v211, v212
	v_mul_f32_e32 v210, v210, v4
	v_mul_f32_e32 v211, v211, v5
	v_cvt_pk_bf16_f32 v18, v210, v211
	v_lshlrev_b32_e32 v210, 16, v19
	v_and_b32_e32 v211, 0xffff0000, v19
	v_mul_f32_e32 v210, v210, v212
	v_mul_f32_e32 v211, v211, v212
	v_mul_f32_e32 v210, v210, v6
	v_mul_f32_e32 v211, v211, v7
	v_cvt_pk_bf16_f32 v19, v210, v211
	v_lshlrev_b32_e32 v210, 16, v20
	v_and_b32_e32 v211, 0xffff0000, v20
	v_mul_f32_e32 v210, v210, v212
	v_mul_f32_e32 v211, v211, v212
	v_mul_f32_e32 v210, v210, v8
	v_mul_f32_e32 v211, v211, v9
	v_cvt_pk_bf16_f32 v20, v210, v211
	v_lshlrev_b32_e32 v210, 16, v21
	v_and_b32_e32 v211, 0xffff0000, v21
	v_mul_f32_e32 v210, v210, v212
	v_mul_f32_e32 v211, v211, v212
	v_mul_f32_e32 v210, v210, v10
; __device__ __forceinline__ unsigned cvt_pk_bf16(float lo, float hi) { unsigned r; asm volatile("v_cvt_pk_bf16_f32 %0, %1, %2" : "=v"(r) : "v"(lo), "v"(hi)); return r; }
; __device__ __forceinline__ void rms_row(const f32x4 (&v)[4], const float* g, int lane, float& rs, f32x4 (&y)[4]) {
;     float s = 0.f;
; #pragma unroll
;     for (int j = 0; j < 4; ++j) s += (v[j].x * v[j].x + v[j].y * v[j].y) + (v[j].z * v[j].z + v[j].w * v[j].w);
;     rs = __builtin_amdgcn_rsqf(wave_sum(s) * (1.f / DM) + EPS);
; #pragma unroll
;     for (int j = 0; j < 4; ++j) { const f32x4 gv = *((const f32x4*)g + lane + 64 * j); y[j] = v[j] * rs * gv; }
; }
; __device__ __forceinline__ void load_bf16_row(const bf16* row, int lane, f32x4 (&v)[4]) {
;     const u32x2* p = (const u32x2*)row + lane;
; #pragma unroll
;     for (int j = 0; j < 4; ++j) { const u32x2 w = p[64 * j]; v[j] = (f32x4){bflo(w.x), bfhi(w.x), bflo(w.y), bfhi(w.y)}; }
; }
; __device__ __forceinline__ void store_bf16_row(bf16* orow, int lane, const f32x4 (&y)[4]) {
;     u32x2* o8 = (u32x2*)orow + lane;
; #pragma unroll
;     for (int j = 0; j < 4; ++j) { u32x2 w; w.x = cvt_pk_bf16(y[j].x, y[j].y); w.y = cvt_pk_bf16(y[j].z, y[j].w); o8[64 * j] = w; }
; }
	v_mul_f32_e32 v211, v211, v11
	v_cvt_pk_bf16_f32 v21, v210, v211
	v_lshlrev_b32_e32 v210, 16, v22
	v_and_b32_e32 v211, 0xffff0000, v22
	v_mul_f32_e32 v210, v210, v212
	v_mul_f32_e32 v211, v211, v212
	v_mul_f32_e32 v210, v210, v12
	v_mul_f32_e32 v211, v211, v13
	v_cvt_pk_bf16_f32 v22, v210, v211
	v_lshlrev_b32_e32 v210, 16, v23
	v_and_b32_e32 v211, 0xffff0000, v23
	v_mul_f32_e32 v210, v210, v212
	v_mul_f32_e32 v211, v211, v212
	v_mul_f32_e32 v210, v210, v14
	v_mul_f32_e32 v211, v211, v15
	v_cvt_pk_bf16_f32 v23, v210, v211
	s_add_u32 s12, s2, 0x5300000
	s_addc_u32 s13, s3, 0
	global_store_dwordx4 v184, v[16:19], s[12:13]
	global_store_dwordx4 v184, v[20:23], s[12:13] offset:1024
	v_lshlrev_b32_e32 v214, 16, v24
	v_and_b32_e32 v215, 0xffff0000, v24
	v_mul_f32_e32 v214, v214, v216
	v_mul_f32_e32 v215, v215, v216
	v_mul_f32_e32 v214, v214, v0
	v_mul_f32_e32 v215, v215, v1
	v_cvt_pk_bf16_f32 v24, v214, v215
	v_lshlrev_b32_e32 v214, 16, v25
	v_and_b32_e32 v215, 0xffff0000, v25
	v_mul_f32_e32 v214, v214, v216
	v_mul_f32_e32 v215, v215, v216
	v_mul_f32_e32 v214, v214, v2
	v_mul_f32_e32 v215, v215, v3
	v_cvt_pk_bf16_f32 v25, v214, v215
	v_lshlrev_b32_e32 v214, 16, v26
	v_and_b32_e32 v215, 0xffff0000, v26
	v_mul_f32_e32 v214, v214, v216
	v_mul_f32_e32 v215, v215, v216
	v_mul_f32_e32 v214, v214, v4
	v_mul_f32_e32 v215, v215, v5
	v_cvt_pk_bf16_f32 v26, v214, v215
	v_lshlrev_b32_e32 v214, 16, v27
	v_and_b32_e32 v215, 0xffff0000, v27
	v_mul_f32_e32 v214, v214, v216
	v_mul_f32_e32 v215, v215, v216
	v_mul_f32_e32 v214, v214, v6
	v_mul_f32_e32 v215, v215, v7
	v_cvt_pk_bf16_f32 v27, v214, v215
	v_lshlrev_b32_e32 v214, 16, v28
	v_and_b32_e32 v215, 0xffff0000, v28
	v_mul_f32_e32 v214, v214, v216
	v_mul_f32_e32 v215, v215, v216
	v_mul_f32_e32 v214, v214, v8
	v_mul_f32_e32 v215, v215, v9
	v_cvt_pk_bf16_f32 v28, v214, v215
	v_lshlrev_b32_e32 v214, 16, v29
	v_and_b32_e32 v215, 0xffff0000, v29
	v_mul_f32_e32 v214, v214, v216
	v_mul_f32_e32 v215, v215, v216
	v_mul_f32_e32 v214, v214, v10
	v_mul_f32_e32 v215, v215, v11
	v_cvt_pk_bf16_f32 v29, v214, v215
	v_lshlrev_b32_e32 v214, 16, v30
	v_and_b32_e32 v215, 0xffff0000, v30
	v_mul_f32_e32 v214, v214, v216
	v_mul_f32_e32 v215, v215, v216
	v_mul_f32_e32 v214, v214, v12
	v_mul_f32_e32 v215, v215, v13
	v_cvt_pk_bf16_f32 v30, v214, v215
	v_lshlrev_b32_e32 v214, 16, v31
	v_and_b32_e32 v215, 0xffff0000, v31
	v_mul_f32_e32 v214, v214, v216
	v_mul_f32_e32 v215, v215, v216
	v_mul_f32_e32 v214, v214, v14
	v_mul_f32_e32 v215, v215, v15
	v_cvt_pk_bf16_f32 v31, v214, v215
	s_add_u32 s12, s2, 0x5700000
	s_addc_u32 s13, s3, 0
	global_store_dwordx4 v184, v[24:27], s[12:13]
	global_store_dwordx4 v184, v[28:31], s[12:13] offset:1024
	v_lshlrev_b32_e32 v218, 16, v32
	v_and_b32_e32 v219, 0xffff0000, v32
	v_mul_f32_e32 v218, v218, v220
	v_mul_f32_e32 v219, v219, v220
	v_mul_f32_e32 v218, v218, v0
	v_mul_f32_e32 v219, v219, v1
	v_cvt_pk_bf16_f32 v32, v218, v219
	v_lshlrev_b32_e32 v218, 16, v33
	v_and_b32_e32 v219, 0xffff0000, v33
	v_mul_f32_e32 v218, v218, v220
	v_mul_f32_e32 v219, v219, v220
	v_mul_f32_e32 v218, v218, v2
	v_mul_f32_e32 v219, v219, v3
	v_cvt_pk_bf16_f32 v33, v218, v219
	v_lshlrev_b32_e32 v218, 16, v34
	v_and_b32_e32 v219, 0xffff0000, v34
	v_mul_f32_e32 v218, v218, v220
	v_mul_f32_e32 v219, v219, v220
	v_mul_f32_e32 v218, v218, v4
	v_mul_f32_e32 v219, v219, v5
	v_cvt_pk_bf16_f32 v34, v218, v219
	v_lshlrev_b32_e32 v218, 16, v35
	v_and_b32_e32 v219, 0xffff0000, v35
	v_mul_f32_e32 v218, v218, v220
	v_mul_f32_e32 v219, v219, v220
	v_mul_f32_e32 v218, v218, v6
	v_mul_f32_e32 v219, v219, v7
	v_cvt_pk_bf16_f32 v35, v218, v219
	v_lshlrev_b32_e32 v218, 16, v36
	v_and_b32_e32 v219, 0xffff0000, v36
	v_mul_f32_e32 v218, v218, v220
	v_mul_f32_e32 v219, v219, v220
	v_mul_f32_e32 v218, v218, v8
	v_mul_f32_e32 v219, v219, v9
	v_cvt_pk_bf16_f32 v36, v218, v219
	v_lshlrev_b32_e32 v218, 16, v37
	v_and_b32_e32 v219, 0xffff0000, v37
	v_mul_f32_e32 v218, v218, v220
	v_mul_f32_e32 v219, v219, v220
	v_mul_f32_e32 v218, v218, v10
	v_mul_f32_e32 v219, v219, v11
	v_cvt_pk_bf16_f32 v37, v218, v219
	v_lshlrev_b32_e32 v218, 16, v38
	v_and_b32_e32 v219, 0xffff0000, v38
	v_mul_f32_e32 v218, v218, v220
	v_mul_f32_e32 v219, v219, v220
	v_mul_f32_e32 v218, v218, v12
	v_mul_f32_e32 v219, v219, v13
	v_cvt_pk_bf16_f32 v38, v218, v219
	v_lshlrev_b32_e32 v218, 16, v39
	v_and_b32_e32 v219, 0xffff0000, v39
	v_mul_f32_e32 v218, v218, v220
	v_mul_f32_e32 v219, v219, v220
	v_mul_f32_e32 v218, v218, v14
	v_mul_f32_e32 v219, v219, v15
	v_cvt_pk_bf16_f32 v39, v218, v219
	s_add_u32 s12, s2, 0x5b00000
	s_addc_u32 s13, s3, 0
	global_store_dwordx4 v184, v[32:35], s[12:13]
	global_store_dwordx4 v184, v[36:39], s[12:13] offset:1024
	v_lshlrev_b32_e32 v222, 16, v40
	v_and_b32_e32 v223, 0xffff0000, v40
	v_mul_f32_e32 v222, v222, v224
	v_mul_f32_e32 v223, v223, v224
	v_mul_f32_e32 v222, v222, v0
	v_mul_f32_e32 v223, v223, v1
	v_cvt_pk_bf16_f32 v40, v222, v223
	v_lshlrev_b32_e32 v222, 16, v41
	v_and_b32_e32 v223, 0xffff0000, v41
	v_mul_f32_e32 v222, v222, v224
	v_mul_f32_e32 v223, v223, v224
	v_mul_f32_e32 v222, v222, v2
	v_mul_f32_e32 v223, v223, v3
	v_cvt_pk_bf16_f32 v41, v222, v223
	v_lshlrev_b32_e32 v222, 16, v42
	v_and_b32_e32 v223, 0xffff0000, v42
	v_mul_f32_e32 v222, v222, v224
	v_mul_f32_e32 v223, v223, v224
	v_mul_f32_e32 v222, v222, v4
	v_mul_f32_e32 v223, v223, v5
	v_cvt_pk_bf16_f32 v42, v222, v223
	v_lshlrev_b32_e32 v222, 16, v43
	v_and_b32_e32 v223, 0xffff0000, v43
	v_mul_f32_e32 v222, v222, v224
	v_mul_f32_e32 v223, v223, v224
	v_mul_f32_e32 v222, v222, v6
	v_mul_f32_e32 v223, v223, v7
	v_cvt_pk_bf16_f32 v43, v222, v223
	v_lshlrev_b32_e32 v222, 16, v44
	v_and_b32_e32 v223, 0xffff0000, v44
	v_mul_f32_e32 v222, v222, v224
	v_mul_f32_e32 v223, v223, v224
	v_mul_f32_e32 v222, v222, v8
	v_mul_f32_e32 v223, v223, v9
	v_cvt_pk_bf16_f32 v44, v222, v223
	v_lshlrev_b32_e32 v222, 16, v45
	v_and_b32_e32 v223, 0xffff0000, v45
	v_mul_f32_e32 v222, v222, v224
	v_mul_f32_e32 v223, v223, v224
	v_mul_f32_e32 v222, v222, v10
	v_mul_f32_e32 v223, v223, v11
	v_cvt_pk_bf16_f32 v45, v222, v223
	v_lshlrev_b32_e32 v222, 16, v46
	v_and_b32_e32 v223, 0xffff0000, v46
	v_mul_f32_e32 v222, v222, v224
	v_mul_f32_e32 v223, v223, v224
	v_mul_f32_e32 v222, v222, v12
	v_mul_f32_e32 v223, v223, v13
	v_cvt_pk_bf16_f32 v46, v222, v223
	v_lshlrev_b32_e32 v222, 16, v47
	v_and_b32_e32 v223, 0xffff0000, v47
	v_mul_f32_e32 v222, v222, v224
	v_mul_f32_e32 v223, v223, v224
	v_mul_f32_e32 v222, v222, v14
	v_mul_f32_e32 v223, v223, v15
	v_cvt_pk_bf16_f32 v47, v222, v223
	s_add_u32 s12, s2, 0x5f00000
	s_addc_u32 s13, s3, 0
	global_store_dwordx4 v184, v[40:43], s[12:13]
	global_store_dwordx4 v184, v[44:47], s[12:13] offset:1024
	s_waitcnt vmcnt(8)
; __device__ __forceinline__ void rms_row(const f32x4 (&v)[4], const float* g, int lane, float& rs, f32x4 (&y)[4]) {
;     float s = 0.f;
; #pragma unroll
;     for (int j = 0; j < 4; ++j) s += (v[j].x * v[j].x + v[j].y * v[j].y) + (v[j].z * v[j].z + v[j].w * v[j].w);
;     rs = __builtin_amdgcn_rsqf(wave_sum(s) * (1.f / DM) + EPS);
; #pragma unroll
;     for (int j = 0; j < 4; ++j) { const f32x4 gv = *((const f32x4*)g + lane + 64 * j); y[j] = v[j] * rs * gv; }
; }
	v_lshlrev_b32_e32 v210, 16, v48
	v_and_b32_e32 v211, 0xffff0000, v48
	v_mul_f32_e32 v212, v210, v210
	v_mul_f32_e32 v213, v211, v211
	v_lshlrev_b32_e32 v214, 16, v56
	v_and_b32_e32 v215, 0xffff0000, v56
	v_mul_f32_e32 v216, v214, v214
	v_mul_f32_e32 v217, v215, v215
	v_lshlrev_b32_e32 v218, 16, v64
	v_and_b32_e32 v219, 0xffff0000, v64
	v_mul_f32_e32 v220, v218, v218
	v_mul_f32_e32 v221, v219, v219
	v_lshlrev_b32_e32 v222, 16, v72
	v_and_b32_e32 v223, 0xffff0000, v72
	v_mul_f32_e32 v224, v222, v222
	v_mul_f32_e32 v225, v223, v223
	v_lshlrev_b32_e32 v210, 16, v49
	v_and_b32_e32 v211, 0xffff0000, v49
	v_fmac_f32_e32 v212, v210, v210
	v_fmac_f32_e32 v213, v211, v211
	v_lshlrev_b32_e32 v214, 16, v57
	v_and_b32_e32 v215, 0xffff0000, v57
	v_fmac_f32_e32 v216, v214, v214
	v_fmac_f32_e32 v217, v215, v215
	v_lshlrev_b32_e32 v218, 16, v65
	v_and_b32_e32 v219, 0xffff0000, v65
	v_fmac_f32_e32 v220, v218, v218
	v_fmac_f32_e32 v221, v219, v219
	v_lshlrev_b32_e32 v222, 16, v73
	v_and_b32_e32 v223, 0xffff0000, v73
	v_fmac_f32_e32 v224, v222, v222
	v_fmac_f32_e32 v225, v223, v223
	v_lshlrev_b32_e32 v210, 16, v50
	v_and_b32_e32 v211, 0xffff0000, v50
	v_fmac_f32_e32 v212, v210, v210
	v_fmac_f32_e32 v213, v211, v211
	v_lshlrev_b32_e32 v214, 16, v58
	v_and_b32_e32 v215, 0xffff0000, v58
	v_fmac_f32_e32 v216, v214, v214
	v_fmac_f32_e32 v217, v215, v215
	v_lshlrev_b32_e32 v218, 16, v66
	v_and_b32_e32 v219, 0xffff0000, v66
	v_fmac_f32_e32 v220, v218, v218
	v_fmac_f32_e32 v221, v219, v219
	v_lshlrev_b32_e32 v222, 16, v74
	v_and_b32_e32 v223, 0xffff0000, v74
	v_fmac_f32_e32 v224, v222, v222
	v_fmac_f32_e32 v225, v223, v223
	v_lshlrev_b32_e32 v210, 16, v51
	v_and_b32_e32 v211, 0xffff0000, v51
	v_fmac_f32_e32 v212, v210, v210
	v_fmac_f32_e32 v213, v211, v211
	v_lshlrev_b32_e32 v214, 16, v59
	v_and_b32_e32 v215, 0xffff0000, v59
	v_fmac_f32_e32 v216, v214, v214
	v_fmac_f32_e32 v217, v215, v215
	v_lshlrev_b32_e32 v218, 16, v67
	v_and_b32_e32 v219, 0xffff0000, v67
	v_fmac_f32_e32 v220, v218, v218
	v_fmac_f32_e32 v221, v219, v219
	v_lshlrev_b32_e32 v222, 16, v75
	v_and_b32_e32 v223, 0xffff0000, v75
	v_fmac_f32_e32 v224, v222, v222
	v_fmac_f32_e32 v225, v223, v223
	v_lshlrev_b32_e32 v210, 16, v52
	v_and_b32_e32 v211, 0xffff0000, v52
	v_fmac_f32_e32 v212, v210, v210
	v_fmac_f32_e32 v213, v211, v211
	v_lshlrev_b32_e32 v214, 16, v60
	v_and_b32_e32 v215, 0xffff0000, v60
	v_fmac_f32_e32 v216, v214, v214
	v_fmac_f32_e32 v217, v215, v215
	v_lshlrev_b32_e32 v218, 16, v68
	v_and_b32_e32 v219, 0xffff0000, v68
	v_fmac_f32_e32 v220, v218, v218
	v_fmac_f32_e32 v221, v219, v219
	v_lshlrev_b32_e32 v222, 16, v76
	v_and_b32_e32 v223, 0xffff0000, v76
	v_fmac_f32_e32 v224, v222, v222
	v_fmac_f32_e32 v225, v223, v223
	v_lshlrev_b32_e32 v210, 16, v53
	v_and_b32_e32 v211, 0xffff0000, v53
	v_fmac_f32_e32 v212, v210, v210
	v_fmac_f32_e32 v213, v211, v211
	v_lshlrev_b32_e32 v214, 16, v61
	v_and_b32_e32 v215, 0xffff0000, v61
	v_fmac_f32_e32 v216, v214, v214
	v_fmac_f32_e32 v217, v215, v215
	v_lshlrev_b32_e32 v218, 16, v69
	v_and_b32_e32 v219, 0xffff0000, v69
	v_fmac_f32_e32 v220, v218, v218
	v_fmac_f32_e32 v221, v219, v219
	v_lshlrev_b32_e32 v222, 16, v77
	v_and_b32_e32 v223, 0xffff0000, v77
	v_fmac_f32_e32 v224, v222, v222
	v_fmac_f32_e32 v225, v223, v223
	v_lshlrev_b32_e32 v210, 16, v54
	v_and_b32_e32 v211, 0xffff0000, v54
	v_fmac_f32_e32 v212, v210, v210
	v_fmac_f32_e32 v213, v211, v211
	v_lshlrev_b32_e32 v214, 16, v62
	v_and_b32_e32 v215, 0xffff0000, v62
	v_fmac_f32_e32 v216, v214, v214
	v_fmac_f32_e32 v217, v215, v215
	v_lshlrev_b32_e32 v218, 16, v70
	v_and_b32_e32 v219, 0xffff0000, v70
	v_fmac_f32_e32 v220, v218, v218
	v_fmac_f32_e32 v221, v219, v219
	v_lshlrev_b32_e32 v222, 16, v78
	v_and_b32_e32 v223, 0xffff0000, v78
	v_fmac_f32_e32 v224, v222, v222
	v_fmac_f32_e32 v225, v223, v223
	v_lshlrev_b32_e32 v210, 16, v55
	v_and_b32_e32 v211, 0xffff0000, v55
	v_fmac_f32_e32 v212, v210, v210
	v_fmac_f32_e32 v213, v211, v211
	v_lshlrev_b32_e32 v214, 16, v63
	v_and_b32_e32 v215, 0xffff0000, v63
	v_fmac_f32_e32 v216, v214, v214
	v_fmac_f32_e32 v217, v215, v215
	v_lshlrev_b32_e32 v218, 16, v71
	v_and_b32_e32 v219, 0xffff0000, v71
	v_fmac_f32_e32 v220, v218, v218
	v_fmac_f32_e32 v221, v219, v219
	v_lshlrev_b32_e32 v222, 16, v79
	v_and_b32_e32 v223, 0xffff0000, v79
	v_fmac_f32_e32 v224, v222, v222
	v_fmac_f32_e32 v225, v223, v223
	v_add_f32_e32 v212, v212, v213
	v_add_f32_e32 v216, v216, v217
	v_add_f32_e32 v220, v220, v221
	v_add_f32_e32 v224, v224, v225
	ds_bpermute_b32 v210, v176, v212
	ds_bpermute_b32 v214, v176, v216
	ds_bpermute_b32 v218, v176, v220
	ds_bpermute_b32 v222, v176, v224
	s_waitcnt lgkmcnt(0)
	v_add_f32_e32 v212, v212, v210
	v_add_f32_e32 v216, v216, v214
	v_add_f32_e32 v220, v220, v218
	v_add_f32_e32 v224, v224, v222
	ds_bpermute_b32 v210, v177, v212
	ds_bpermute_b32 v214, v177, v216
	ds_bpermute_b32 v218, v177, v220
	ds_bpermute_b32 v222, v177, v224
	s_waitcnt lgkmcnt(0)
	v_add_f32_e32 v212, v212, v210
	v_add_f32_e32 v216, v216, v214
	v_add_f32_e32 v220, v220, v218
	v_add_f32_e32 v224, v224, v222
	ds_bpermute_b32 v210, v178, v212
	ds_bpermute_b32 v214, v178, v216
	ds_bpermute_b32 v218, v178, v220
	ds_bpermute_b32 v222, v178, v224
	s_waitcnt lgkmcnt(0)
	v_add_f32_e32 v212, v212, v210
	v_add_f32_e32 v216, v216, v214
	v_add_f32_e32 v220, v220, v218
	v_add_f32_e32 v224, v224, v222
	ds_bpermute_b32 v210, v179, v212
	ds_bpermute_b32 v214, v179, v216
	ds_bpermute_b32 v218, v179, v220
	ds_bpermute_b32 v222, v179, v224
	s_waitcnt lgkmcnt(0)
	v_add_f32_e32 v212, v212, v210
	v_add_f32_e32 v216, v216, v214
	v_add_f32_e32 v220, v220, v218
	v_add_f32_e32 v224, v224, v222
	ds_bpermute_b32 v210, v180, v212
	ds_bpermute_b32 v214, v180, v216
	ds_bpermute_b32 v218, v180, v220
	ds_bpermute_b32 v222, v180, v224
	s_waitcnt lgkmcnt(0)
; __device__ __forceinline__ unsigned cvt_pk_bf16(float lo, float hi) { unsigned r; asm volatile("v_cvt_pk_bf16_f32 %0, %1, %2" : "=v"(r) : "v"(lo), "v"(hi)); return r; }
; __device__ __forceinline__ void rms_row(const f32x4 (&v)[4], const float* g, int lane, float& rs, f32x4 (&y)[4]) {
;     float s = 0.f;
; #pragma unroll
;     for (int j = 0; j < 4; ++j) s += (v[j].x * v[j].x + v[j].y * v[j].y) + (v[j].z * v[j].z + v[j].w * v[j].w);
;     rs = __builtin_amdgcn_rsqf(wave_sum(s) * (1.f / DM) + EPS);
; #pragma unroll
;     for (int j = 0; j < 4; ++j) { const f32x4 gv = *((const f32x4*)g + lane + 64 * j); y[j] = v[j] * rs * gv; }
; }
; __device__ __forceinline__ void load_bf16_row(const bf16* row, int lane, f32x4 (&v)[4]) {
;     const u32x2* p = (const u32x2*)row + lane;
; #pragma unroll
;     for (int j = 0; j < 4; ++j) { const u32x2 w = p[64 * j]; v[j] = (f32x4){bflo(w.x), bfhi(w.x), bflo(w.y), bfhi(w.y)}; }
; }
; __device__ __forceinline__ void store_bf16_row(bf16* orow, int lane, const f32x4 (&y)[4]) {
;     u32x2* o8 = (u32x2*)orow + lane;
; #pragma unroll
;     for (int j = 0; j < 4; ++j) { u32x2 w; w.x = cvt_pk_bf16(y[j].x, y[j].y); w.y = cvt_pk_bf16(y[j].z, y[j].w); o8[64 * j] = w; }
; }
	v_add_f32_e32 v212, v212, v210
	v_add_f32_e32 v216, v216, v214
	v_add_f32_e32 v220, v220, v218
	v_add_f32_e32 v224, v224, v222
	ds_bpermute_b32 v210, v181, v212
	ds_bpermute_b32 v214, v181, v216
	ds_bpermute_b32 v218, v181, v220
	ds_bpermute_b32 v222, v181, v224
	s_waitcnt lgkmcnt(0)
	v_add_f32_e32 v212, v212, v210
	v_add_f32_e32 v216, v216, v214
	v_add_f32_e32 v220, v220, v218
	v_add_f32_e32 v224, v224, v222
	v_fmamk_f32 v212, v212, 0x3a800000, v207
	v_fmamk_f32 v216, v216, 0x3a800000, v207
	v_fmamk_f32 v220, v220, 0x3a800000, v207
	v_fmamk_f32 v224, v224, 0x3a800000, v207
	v_rsq_f32_e32 v212, v212
	v_rsq_f32_e32 v216, v216
	v_rsq_f32_e32 v220, v220
	v_rsq_f32_e32 v224, v224
	s_nop 1
	v_lshlrev_b32_e32 v210, 16, v48
	v_and_b32_e32 v211, 0xffff0000, v48
	v_mul_f32_e32 v210, v210, v212
	v_mul_f32_e32 v211, v211, v212
	v_mul_f32_e32 v210, v210, v0
	v_mul_f32_e32 v211, v211, v1
	v_cvt_pk_bf16_f32 v48, v210, v211
	v_lshlrev_b32_e32 v210, 16, v49
	v_and_b32_e32 v211, 0xffff0000, v49
	v_mul_f32_e32 v210, v210, v212
	v_mul_f32_e32 v211, v211, v212
	v_mul_f32_e32 v210, v210, v2
	v_mul_f32_e32 v211, v211, v3
	v_cvt_pk_bf16_f32 v49, v210, v211
	v_lshlrev_b32_e32 v210, 16, v50
	v_and_b32_e32 v211, 0xffff0000, v50
	v_mul_f32_e32 v210, v210, v212
	v_mul_f32_e32 v211, v211, v212
	v_mul_f32_e32 v210, v210, v4
	v_mul_f32_e32 v211, v211, v5
	v_cvt_pk_bf16_f32 v50, v210, v211
	v_lshlrev_b32_e32 v210, 16, v51
	v_and_b32_e32 v211, 0xffff0000, v51
	v_mul_f32_e32 v210, v210, v212
	v_mul_f32_e32 v211, v211, v212
	v_mul_f32_e32 v210, v210, v6
	v_mul_f32_e32 v211, v211, v7
	v_cvt_pk_bf16_f32 v51, v210, v211
	v_lshlrev_b32_e32 v210, 16, v52
	v_and_b32_e32 v211, 0xffff0000, v52
	v_mul_f32_e32 v210, v210, v212
	v_mul_f32_e32 v211, v211, v212
	v_mul_f32_e32 v210, v210, v8
	v_mul_f32_e32 v211, v211, v9
	v_cvt_pk_bf16_f32 v52, v210, v211
	v_lshlrev_b32_e32 v210, 16, v53
	v_and_b32_e32 v211, 0xffff0000, v53
	v_mul_f32_e32 v210, v210, v212
	v_mul_f32_e32 v211, v211, v212
	v_mul_f32_e32 v210, v210, v10
	v_mul_f32_e32 v211, v211, v11
	v_cvt_pk_bf16_f32 v53, v210, v211
	v_lshlrev_b32_e32 v210, 16, v54
	v_and_b32_e32 v211, 0xffff0000, v54
	v_mul_f32_e32 v210, v210, v212
	v_mul_f32_e32 v211, v211, v212
	v_mul_f32_e32 v210, v210, v12
	v_mul_f32_e32 v211, v211, v13
	v_cvt_pk_bf16_f32 v54, v210, v211
	v_lshlrev_b32_e32 v210, 16, v55
	v_and_b32_e32 v211, 0xffff0000, v55
	v_mul_f32_e32 v210, v210, v212
	v_mul_f32_e32 v211, v211, v212
	v_mul_f32_e32 v210, v210, v14
	v_mul_f32_e32 v211, v211, v15
	v_cvt_pk_bf16_f32 v55, v210, v211
	s_add_u32 s12, s2, 0x6300000
	s_addc_u32 s13, s3, 0
	global_store_dwordx4 v184, v[48:51], s[12:13]
	global_store_dwordx4 v184, v[52:55], s[12:13] offset:1024
	v_lshlrev_b32_e32 v214, 16, v56
	v_and_b32_e32 v215, 0xffff0000, v56
	v_mul_f32_e32 v214, v214, v216
	v_mul_f32_e32 v215, v215, v216
	v_mul_f32_e32 v214, v214, v0
	v_mul_f32_e32 v215, v215, v1
	v_cvt_pk_bf16_f32 v56, v214, v215
	v_lshlrev_b32_e32 v214, 16, v57
	v_and_b32_e32 v215, 0xffff0000, v57
	v_mul_f32_e32 v214, v214, v216
	v_mul_f32_e32 v215, v215, v216
	v_mul_f32_e32 v214, v214, v2
	v_mul_f32_e32 v215, v215, v3
	v_cvt_pk_bf16_f32 v57, v214, v215
	v_lshlrev_b32_e32 v214, 16, v58
	v_and_b32_e32 v215, 0xffff0000, v58
	v_mul_f32_e32 v214, v214, v216
	v_mul_f32_e32 v215, v215, v216
	v_mul_f32_e32 v214, v214, v4
	v_mul_f32_e32 v215, v215, v5
	v_cvt_pk_bf16_f32 v58, v214, v215
	v_lshlrev_b32_e32 v214, 16, v59
	v_and_b32_e32 v215, 0xffff0000, v59
	v_mul_f32_e32 v214, v214, v216
	v_mul_f32_e32 v215, v215, v216
	v_mul_f32_e32 v214, v214, v6
	v_mul_f32_e32 v215, v215, v7
	v_cvt_pk_bf16_f32 v59, v214, v215
	v_lshlrev_b32_e32 v214, 16, v60
	v_and_b32_e32 v215, 0xffff0000, v60
	v_mul_f32_e32 v214, v214, v216
	v_mul_f32_e32 v215, v215, v216
	v_mul_f32_e32 v214, v214, v8
	v_mul_f32_e32 v215, v215, v9
	v_cvt_pk_bf16_f32 v60, v214, v215
	v_lshlrev_b32_e32 v214, 16, v61
	v_and_b32_e32 v215, 0xffff0000, v61
	v_mul_f32_e32 v214, v214, v216
	v_mul_f32_e32 v215, v215, v216
	v_mul_f32_e32 v214, v214, v10
	v_mul_f32_e32 v215, v215, v11
	v_cvt_pk_bf16_f32 v61, v214, v215
	v_lshlrev_b32_e32 v214, 16, v62
	v_and_b32_e32 v215, 0xffff0000, v62
	v_mul_f32_e32 v214, v214, v216
	v_mul_f32_e32 v215, v215, v216
	v_mul_f32_e32 v214, v214, v12
	v_mul_f32_e32 v215, v215, v13
	v_cvt_pk_bf16_f32 v62, v214, v215
	v_lshlrev_b32_e32 v214, 16, v63
	v_and_b32_e32 v215, 0xffff0000, v63
	v_mul_f32_e32 v214, v214, v216
	v_mul_f32_e32 v215, v215, v216
	v_mul_f32_e32 v214, v214, v14
	v_mul_f32_e32 v215, v215, v15
	v_cvt_pk_bf16_f32 v63, v214, v215
	s_add_u32 s12, s2, 0x6700000
	s_addc_u32 s13, s3, 0
	global_store_dwordx4 v184, v[56:59], s[12:13]
	global_store_dwordx4 v184, v[60:63], s[12:13] offset:1024
	v_lshlrev_b32_e32 v218, 16, v64
	v_and_b32_e32 v219, 0xffff0000, v64
	v_mul_f32_e32 v218, v218, v220
	v_mul_f32_e32 v219, v219, v220
	v_mul_f32_e32 v218, v218, v0
	v_mul_f32_e32 v219, v219, v1
	v_cvt_pk_bf16_f32 v64, v218, v219
	v_lshlrev_b32_e32 v218, 16, v65
	v_and_b32_e32 v219, 0xffff0000, v65
	v_mul_f32_e32 v218, v218, v220
	v_mul_f32_e32 v219, v219, v220
	v_mul_f32_e32 v218, v218, v2
	v_mul_f32_e32 v219, v219, v3
	v_cvt_pk_bf16_f32 v65, v218, v219
	v_lshlrev_b32_e32 v218, 16, v66
	v_and_b32_e32 v219, 0xffff0000, v66
	v_mul_f32_e32 v218, v218, v220
	v_mul_f32_e32 v219, v219, v220
	v_mul_f32_e32 v218, v218, v4
	v_mul_f32_e32 v219, v219, v5
	v_cvt_pk_bf16_f32 v66, v218, v219
	v_lshlrev_b32_e32 v218, 16, v67
	v_and_b32_e32 v219, 0xffff0000, v67
	v_mul_f32_e32 v218, v218, v220
	v_mul_f32_e32 v219, v219, v220
	v_mul_f32_e32 v218, v218, v6
	v_mul_f32_e32 v219, v219, v7
	v_cvt_pk_bf16_f32 v67, v218, v219
	v_lshlrev_b32_e32 v218, 16, v68
; __device__ __forceinline__ unsigned cvt_pk_bf16(float lo, float hi) { unsigned r; asm volatile("v_cvt_pk_bf16_f32 %0, %1, %2" : "=v"(r) : "v"(lo), "v"(hi)); return r; }
; __device__ __forceinline__ void rms_row(const f32x4 (&v)[4], const float* g, int lane, float& rs, f32x4 (&y)[4]) {
;     ...
;     for (int j = 0; j < 4; ++j) { const f32x4 gv = *((const f32x4*)g + lane + 64 * j); y[j] = v[j] * rs * gv; }
; }
; __device__ __forceinline__ void load_bf16_row(const bf16* row, int lane, f32x4 (&v)[4]) {
;     const u32x2* p = (const u32x2*)row + lane;
; #pragma unroll
;     for (int j = 0; j < 4; ++j) { const u32x2 w = p[64 * j]; v[j] = (f32x4){bflo(w.x), bfhi(w.x), bflo(w.y), bfhi(w.y)}; }
; }
; __device__ __forceinline__ void store_bf16_row(bf16* orow, int lane, const f32x4 (&y)[4]) {
;     u32x2* o8 = (u32x2*)orow + lane;
; #pragma unroll
;     for (int j = 0; j < 4; ++j) { u32x2 w; w.x = cvt_pk_bf16(y[j].x, y[j].y); w.y = cvt_pk_bf16(y[j].z, y[j].w); o8[64 * j] = w; }
; }
; template <int NSLICE> __device__ __forceinline__ void rms_phase(ArgP a, const float* g, bool final_out, int G) {
;     ...
;     for (int t = (NGW - 1 - gw); t < M_REAL - R_META; t += NGW) {
;         const int m = R_META + t;
;         if (final_out && m < R_SAMP) continue;
;         f32x4 v[4]; load_bf16_row(H + (size_t)m * DM, lane, v);
;         const bf16* PART = (const bf16*)(a->ws + WS_P + 6 * ROWBUF) + (size_t)t * DM;
; #pragma unroll
;         for (int sl = 0; sl < NSLICE; ++sl) {
;             f32x4 pv[4]; load_bf16_row(PART + (size_t)sl * (MP - R_META) * DM, lane, pv);
; #pragma unroll
;             for (int j = 0; j < 4; ++j) v[j] = v[j] + pv[j];
;         }
;         if (!final_out) store_bf16_row(H + (size_t)m * DM, lane, v);
	v_and_b32_e32 v219, 0xffff0000, v68
	v_mul_f32_e32 v218, v218, v220
	v_mul_f32_e32 v219, v219, v220
	v_mul_f32_e32 v218, v218, v8
	v_mul_f32_e32 v219, v219, v9
	v_cvt_pk_bf16_f32 v68, v218, v219
	v_lshlrev_b32_e32 v218, 16, v69
	v_and_b32_e32 v219, 0xffff0000, v69
	v_mul_f32_e32 v218, v218, v220
	v_mul_f32_e32 v219, v219, v220
	v_mul_f32_e32 v218, v218, v10
	v_mul_f32_e32 v219, v219, v11
	v_cvt_pk_bf16_f32 v69, v218, v219
	v_lshlrev_b32_e32 v218, 16, v70
	v_and_b32_e32 v219, 0xffff0000, v70
	v_mul_f32_e32 v218, v218, v220
	v_mul_f32_e32 v219, v219, v220
	v_mul_f32_e32 v218, v218, v12
	v_mul_f32_e32 v219, v219, v13
	v_cvt_pk_bf16_f32 v70, v218, v219
	v_lshlrev_b32_e32 v218, 16, v71
	v_and_b32_e32 v219, 0xffff0000, v71
	v_mul_f32_e32 v218, v218, v220
	v_mul_f32_e32 v219, v219, v220
	v_mul_f32_e32 v218, v218, v14
	v_mul_f32_e32 v219, v219, v15
	v_cvt_pk_bf16_f32 v71, v218, v219
	s_add_u32 s12, s2, 0x6b00000
	s_addc_u32 s13, s3, 0
	global_store_dwordx4 v184, v[64:67], s[12:13]
	global_store_dwordx4 v184, v[68:71], s[12:13] offset:1024
	v_lshlrev_b32_e32 v222, 16, v72
	v_and_b32_e32 v223, 0xffff0000, v72
	v_mul_f32_e32 v222, v222, v224
	v_mul_f32_e32 v223, v223, v224
	v_mul_f32_e32 v222, v222, v0
	v_mul_f32_e32 v223, v223, v1
	v_cvt_pk_bf16_f32 v72, v222, v223
	v_lshlrev_b32_e32 v222, 16, v73
	v_and_b32_e32 v223, 0xffff0000, v73
	v_mul_f32_e32 v222, v222, v224
	v_mul_f32_e32 v223, v223, v224
	v_mul_f32_e32 v222, v222, v2
	v_mul_f32_e32 v223, v223, v3
	v_cvt_pk_bf16_f32 v73, v222, v223
	v_lshlrev_b32_e32 v222, 16, v74
	v_and_b32_e32 v223, 0xffff0000, v74
	v_mul_f32_e32 v222, v222, v224
	v_mul_f32_e32 v223, v223, v224
	v_mul_f32_e32 v222, v222, v4
	v_mul_f32_e32 v223, v223, v5
	v_cvt_pk_bf16_f32 v74, v222, v223
	v_lshlrev_b32_e32 v222, 16, v75
	v_and_b32_e32 v223, 0xffff0000, v75
	v_mul_f32_e32 v222, v222, v224
	v_mul_f32_e32 v223, v223, v224
	v_mul_f32_e32 v222, v222, v6
	v_mul_f32_e32 v223, v223, v7
	v_cvt_pk_bf16_f32 v75, v222, v223
	v_lshlrev_b32_e32 v222, 16, v76
	v_and_b32_e32 v223, 0xffff0000, v76
	v_mul_f32_e32 v222, v222, v224
	v_mul_f32_e32 v223, v223, v224
	v_mul_f32_e32 v222, v222, v8
	v_mul_f32_e32 v223, v223, v9
	v_cvt_pk_bf16_f32 v76, v222, v223
	v_lshlrev_b32_e32 v222, 16, v77
	v_and_b32_e32 v223, 0xffff0000, v77
	v_mul_f32_e32 v222, v222, v224
	v_mul_f32_e32 v223, v223, v224
	v_mul_f32_e32 v222, v222, v10
	v_mul_f32_e32 v223, v223, v11
	v_cvt_pk_bf16_f32 v77, v222, v223
	v_lshlrev_b32_e32 v222, 16, v78
	v_and_b32_e32 v223, 0xffff0000, v78
	v_mul_f32_e32 v222, v222, v224
	v_mul_f32_e32 v223, v223, v224
	v_mul_f32_e32 v222, v222, v12
	v_mul_f32_e32 v223, v223, v13
	v_cvt_pk_bf16_f32 v78, v222, v223
	v_lshlrev_b32_e32 v222, 16, v79
	v_and_b32_e32 v223, 0xffff0000, v79
	v_mul_f32_e32 v222, v222, v224
	v_mul_f32_e32 v223, v223, v224
	v_mul_f32_e32 v222, v222, v14
	v_mul_f32_e32 v223, v223, v15
	v_cvt_pk_bf16_f32 v79, v222, v223
	s_add_u32 s12, s2, 0x6f00000
	s_addc_u32 s13, s3, 0
	global_store_dwordx4 v184, v[72:75], s[12:13]
	global_store_dwordx4 v184, v[76:79], s[12:13] offset:1024
	s_cmp_lt_u32 s10, 0x480
	s_cbranch_scc0 .Lrms5_done
	v_lshlrev_b32_e32 v226, 16, v80
	v_and_b32_e32 v227, 0xffff0000, v80
	v_lshlrev_b32_e32 v228, 16, v81
	v_and_b32_e32 v229, 0xffff0000, v81
	v_lshlrev_b32_e32 v230, 16, v82
	v_and_b32_e32 v231, 0xffff0000, v82
	v_lshlrev_b32_e32 v232, 16, v83
	v_and_b32_e32 v233, 0xffff0000, v83
	v_lshlrev_b32_e32 v234, 16, v84
	v_and_b32_e32 v235, 0xffff0000, v84
	v_lshlrev_b32_e32 v236, 16, v85
	v_and_b32_e32 v237, 0xffff0000, v85
	v_lshlrev_b32_e32 v238, 16, v86
	v_and_b32_e32 v239, 0xffff0000, v86
	v_lshlrev_b32_e32 v240, 16, v87
	v_and_b32_e32 v241, 0xffff0000, v87
	v_lshlrev_b32_e32 v242, 16, v88
	v_and_b32_e32 v243, 0xffff0000, v88
	v_add_f32_e32 v226, v226, v242
	v_add_f32_e32 v227, v227, v243
	v_lshlrev_b32_e32 v242, 16, v89
	v_and_b32_e32 v243, 0xffff0000, v89
	v_add_f32_e32 v228, v228, v242
	v_add_f32_e32 v229, v229, v243
	v_lshlrev_b32_e32 v242, 16, v90
	v_and_b32_e32 v243, 0xffff0000, v90
	v_add_f32_e32 v230, v230, v242
	v_add_f32_e32 v231, v231, v243
	v_lshlrev_b32_e32 v242, 16, v91
	v_and_b32_e32 v243, 0xffff0000, v91
	v_add_f32_e32 v232, v232, v242
	v_add_f32_e32 v233, v233, v243
	v_lshlrev_b32_e32 v242, 16, v92
	v_and_b32_e32 v243, 0xffff0000, v92
	v_add_f32_e32 v234, v234, v242
	v_add_f32_e32 v235, v235, v243
	v_lshlrev_b32_e32 v242, 16, v93
	v_and_b32_e32 v243, 0xffff0000, v93
	v_add_f32_e32 v236, v236, v242
	v_add_f32_e32 v237, v237, v243
	v_lshlrev_b32_e32 v242, 16, v94
	v_and_b32_e32 v243, 0xffff0000, v94
	v_add_f32_e32 v238, v238, v242
	v_add_f32_e32 v239, v239, v243
	v_lshlrev_b32_e32 v242, 16, v95
	v_and_b32_e32 v243, 0xffff0000, v95
	v_add_f32_e32 v240, v240, v242
	v_add_f32_e32 v241, v241, v243
	v_lshlrev_b32_e32 v242, 16, v96
	v_and_b32_e32 v243, 0xffff0000, v96
	v_add_f32_e32 v226, v226, v242
	v_add_f32_e32 v227, v227, v243
	v_lshlrev_b32_e32 v242, 16, v97
	v_and_b32_e32 v243, 0xffff0000, v97
	v_add_f32_e32 v228, v228, v242
	v_add_f32_e32 v229, v229, v243
	v_lshlrev_b32_e32 v242, 16, v98
	v_and_b32_e32 v243, 0xffff0000, v98
	v_add_f32_e32 v230, v230, v242
	v_add_f32_e32 v231, v231, v243
	v_lshlrev_b32_e32 v242, 16, v99
	v_and_b32_e32 v243, 0xffff0000, v99
	v_add_f32_e32 v232, v232, v242
	v_add_f32_e32 v233, v233, v243
	v_lshlrev_b32_e32 v242, 16, v100
	v_and_b32_e32 v243, 0xffff0000, v100
	v_add_f32_e32 v234, v234, v242
	v_add_f32_e32 v235, v235, v243
	v_lshlrev_b32_e32 v242, 16, v101
	v_and_b32_e32 v243, 0xffff0000, v101
	v_add_f32_e32 v236, v236, v242
	v_add_f32_e32 v237, v237, v243
	v_lshlrev_b32_e32 v242, 16, v102
	v_and_b32_e32 v243, 0xffff0000, v102
	v_add_f32_e32 v238, v238, v242
; template <int NSLICE> __device__ __forceinline__ void rms_phase(ArgP a, const float* g, bool final_out, int G) {
;     ...
;     for (int t = (NGW - 1 - gw); t < M_REAL - R_META; t += NGW) {
;         const int m = R_META + t;
;         if (final_out && m < R_SAMP) continue;
;         f32x4 v[4]; load_bf16_row(H + (size_t)m * DM, lane, v);
;         const bf16* PART = (const bf16*)(a->ws + WS_P + 6 * ROWBUF) + (size_t)t * DM;
; #pragma unroll
;         for (int sl = 0; sl < NSLICE; ++sl) {
;             f32x4 pv[4]; load_bf16_row(PART + (size_t)sl * (MP - R_META) * DM, lane, pv);
; #pragma unroll
;             for (int j = 0; j < 4; ++j) v[j] = v[j] + pv[j];
;         }
;         if (!final_out) store_bf16_row(H + (size_t)m * DM, lane, v);
;         float rs; f32x4 y[4]; rms_row(v, g, lane, rs, y);
;         if (!final_out) store_bf16_row(XN + (size_t)m * DM, lane, y);
;         else { float* o = a->out + O_YS + (size_t)(m - R_SAMP) * DM;
; #pragma unroll
;             for (int j = 0; j < 4; ++j) *((f32x4*)o + lane + 64 * j) = y[j]; }
;     }
; __device__ __forceinline__ void xcd_barrier(const XcdBarrier& b) {
;     asm volatile("s_waitcnt vmcnt(0)" ::: "memory");
;     __syncthreads();
;     if (threadIdx.x == 0) {
;         unsigned* bar = b.bar;
;         __builtin_amdgcn_s_waitcnt(0);
;         unsigned nloc = b.st[0], nx = b.st[1];
;         if (nloc == 0u) { xcd_barrier_complete(bar, b.x, nloc, nx); b.st[0] = nloc; b.st[1] = nx; }
	v_add_f32_e32 v239, v239, v243
	v_lshlrev_b32_e32 v242, 16, v103
	v_and_b32_e32 v243, 0xffff0000, v103
	v_add_f32_e32 v240, v240, v242
	v_add_f32_e32 v241, v241, v243
	v_lshlrev_b32_e32 v242, 16, v104
	v_and_b32_e32 v243, 0xffff0000, v104
	v_add_f32_e32 v226, v226, v242
	v_add_f32_e32 v227, v227, v243
	v_lshlrev_b32_e32 v242, 16, v105
	v_and_b32_e32 v243, 0xffff0000, v105
	v_add_f32_e32 v228, v228, v242
	v_add_f32_e32 v229, v229, v243
	v_lshlrev_b32_e32 v242, 16, v106
	v_and_b32_e32 v243, 0xffff0000, v106
	v_add_f32_e32 v230, v230, v242
	v_add_f32_e32 v231, v231, v243
	v_lshlrev_b32_e32 v242, 16, v107
	v_and_b32_e32 v243, 0xffff0000, v107
	v_add_f32_e32 v232, v232, v242
	v_add_f32_e32 v233, v233, v243
	v_lshlrev_b32_e32 v242, 16, v108
	v_and_b32_e32 v243, 0xffff0000, v108
	v_add_f32_e32 v234, v234, v242
	v_add_f32_e32 v235, v235, v243
	v_lshlrev_b32_e32 v242, 16, v109
	v_and_b32_e32 v243, 0xffff0000, v109
	v_add_f32_e32 v236, v236, v242
	v_add_f32_e32 v237, v237, v243
	v_lshlrev_b32_e32 v242, 16, v110
	v_and_b32_e32 v243, 0xffff0000, v110
	v_add_f32_e32 v238, v238, v242
	v_add_f32_e32 v239, v239, v243
	v_lshlrev_b32_e32 v242, 16, v111
	v_and_b32_e32 v243, 0xffff0000, v111
	v_add_f32_e32 v240, v240, v242
	v_add_f32_e32 v241, v241, v243
	v_lshlrev_b32_e32 v242, 16, v112
	v_and_b32_e32 v243, 0xffff0000, v112
	v_add_f32_e32 v226, v226, v242
	v_add_f32_e32 v227, v227, v243
	v_lshlrev_b32_e32 v242, 16, v113
	v_and_b32_e32 v243, 0xffff0000, v113
	v_add_f32_e32 v228, v228, v242
	v_add_f32_e32 v229, v229, v243
	v_lshlrev_b32_e32 v242, 16, v114
	v_and_b32_e32 v243, 0xffff0000, v114
	v_add_f32_e32 v230, v230, v242
	v_add_f32_e32 v231, v231, v243
	v_lshlrev_b32_e32 v242, 16, v115
	v_and_b32_e32 v243, 0xffff0000, v115
	v_add_f32_e32 v232, v232, v242
	v_add_f32_e32 v233, v233, v243
	v_lshlrev_b32_e32 v242, 16, v116
	v_and_b32_e32 v243, 0xffff0000, v116
	v_add_f32_e32 v234, v234, v242
	v_add_f32_e32 v235, v235, v243
	v_lshlrev_b32_e32 v242, 16, v117
	v_and_b32_e32 v243, 0xffff0000, v117
	v_add_f32_e32 v236, v236, v242
	v_add_f32_e32 v237, v237, v243
	v_lshlrev_b32_e32 v242, 16, v118
	v_and_b32_e32 v243, 0xffff0000, v118
	v_add_f32_e32 v238, v238, v242
	v_add_f32_e32 v239, v239, v243
	v_lshlrev_b32_e32 v242, 16, v119
	v_and_b32_e32 v243, 0xffff0000, v119
	v_add_f32_e32 v240, v240, v242
	v_add_f32_e32 v241, v241, v243
	v_cvt_pk_bf16_f32 v80, v226, v227
	v_cvt_pk_bf16_f32 v81, v228, v229
	v_cvt_pk_bf16_f32 v82, v230, v231
	v_cvt_pk_bf16_f32 v83, v232, v233
	v_cvt_pk_bf16_f32 v84, v234, v235
	v_cvt_pk_bf16_f32 v85, v236, v237
	v_cvt_pk_bf16_f32 v86, v238, v239
	v_cvt_pk_bf16_f32 v87, v240, v241
	s_add_u32 s12, s2, 0x9580000
	s_addc_u32 s13, s3, 0
	global_store_dwordx4 v185, v[80:83], s[12:13]
	global_store_dwordx4 v185, v[84:87], s[12:13] offset:1024
	v_mul_f32_e32 v244, v226, v226
	v_mul_f32_e32 v245, v227, v227
	v_fmac_f32_e32 v244, v228, v228
	v_fmac_f32_e32 v245, v229, v229
	v_fmac_f32_e32 v244, v230, v230
	v_fmac_f32_e32 v245, v231, v231
	v_fmac_f32_e32 v244, v232, v232
	v_fmac_f32_e32 v245, v233, v233
	v_fmac_f32_e32 v244, v234, v234
	v_fmac_f32_e32 v245, v235, v235
	v_fmac_f32_e32 v244, v236, v236
	v_fmac_f32_e32 v245, v237, v237
	v_fmac_f32_e32 v244, v238, v238
	v_fmac_f32_e32 v245, v239, v239
	v_fmac_f32_e32 v244, v240, v240
	v_fmac_f32_e32 v245, v241, v241
	v_add_f32_e32 v244, v244, v245
	ds_bpermute_b32 v242, v176, v244
	s_waitcnt lgkmcnt(0)
	v_add_f32_e32 v244, v244, v242
	ds_bpermute_b32 v242, v177, v244
	s_waitcnt lgkmcnt(0)
	v_add_f32_e32 v244, v244, v242
	ds_bpermute_b32 v242, v178, v244
	s_waitcnt lgkmcnt(0)
	v_add_f32_e32 v244, v244, v242
	ds_bpermute_b32 v242, v179, v244
	s_waitcnt lgkmcnt(0)
	v_add_f32_e32 v244, v244, v242
	ds_bpermute_b32 v242, v180, v244
	s_waitcnt lgkmcnt(0)
	v_add_f32_e32 v244, v244, v242
	ds_bpermute_b32 v242, v181, v244
	s_waitcnt lgkmcnt(0)
	v_add_f32_e32 v244, v244, v242
	v_fmamk_f32 v244, v244, 0x3a800000, v207
	v_rsq_f32_e32 v244, v244
	s_nop 1
	v_mul_f32_e32 v226, v226, v244
	v_mul_f32_e32 v227, v227, v244
	v_mul_f32_e32 v226, v226, v0
	v_mul_f32_e32 v227, v227, v1
	v_cvt_pk_bf16_f32 v88, v226, v227
	v_mul_f32_e32 v228, v228, v244
	v_mul_f32_e32 v229, v229, v244
	v_mul_f32_e32 v228, v228, v2
	v_mul_f32_e32 v229, v229, v3
	v_cvt_pk_bf16_f32 v89, v228, v229
	v_mul_f32_e32 v230, v230, v244
	v_mul_f32_e32 v231, v231, v244
	v_mul_f32_e32 v230, v230, v4
	v_mul_f32_e32 v231, v231, v5
	v_cvt_pk_bf16_f32 v90, v230, v231
	v_mul_f32_e32 v232, v232, v244
	v_mul_f32_e32 v233, v233, v244
	v_mul_f32_e32 v232, v232, v6
	v_mul_f32_e32 v233, v233, v7
	v_cvt_pk_bf16_f32 v91, v232, v233
	v_mul_f32_e32 v234, v234, v244
	v_mul_f32_e32 v235, v235, v244
	v_mul_f32_e32 v234, v234, v8
	v_mul_f32_e32 v235, v235, v9
	v_cvt_pk_bf16_f32 v92, v234, v235
	v_mul_f32_e32 v236, v236, v244
	v_mul_f32_e32 v237, v237, v244
	v_mul_f32_e32 v236, v236, v10
	v_mul_f32_e32 v237, v237, v11
	v_cvt_pk_bf16_f32 v93, v236, v237
	v_mul_f32_e32 v238, v238, v244
	v_mul_f32_e32 v239, v239, v244
	v_mul_f32_e32 v238, v238, v12
	v_mul_f32_e32 v239, v239, v13
	v_cvt_pk_bf16_f32 v94, v238, v239
	v_mul_f32_e32 v240, v240, v244
	v_mul_f32_e32 v241, v241, v244
	v_mul_f32_e32 v240, v240, v14
	v_mul_f32_e32 v241, v241, v15
	v_cvt_pk_bf16_f32 v95, v240, v241
	s_add_u32 s12, s2, 0x7300000
	s_addc_u32 s13, s3, 0
	global_store_dwordx4 v185, v[88:91], s[12:13]
	global_store_dwordx4 v185, v[92:95], s[12:13] offset:1024
.Lrms5_done:
.LBB0_1061:
	s_movk_i32 s46, 0x47f
	s_or_b64 exec, exec, s[0:1]
	v_readlane_b32 s36, v254, 10
	v_readlane_b32 s33, v254, 12
	v_readlane_b32 s37, v254, 11
	s_waitcnt vmcnt(0)
	s_waitcnt lgkmcnt(0)
	s_barrier
	s_mov_b64 s[34:35], exec
	v_readlane_b32 s0, v254, 13
	v_readlane_b32 s1, v254, 14
	s_and_b64 s[0:1], s[34:35], s[0:1]
	s_mov_b64 exec, s[0:1]
	s_cbranch_execz .LBB0_1105
	v_readlane_b32 s0, v254, 58
	s_waitcnt vmcnt(0) expcnt(0) lgkmcnt(0)
	s_nop 0
	v_mov_b32_e32 v0, s0
	ds_read_b32 v2, v0
	v_readlane_b32 s0, v254, 59
	s_waitcnt lgkmcnt(0)
	v_cmp_ne_u32_e32 vcc, 0, v2
	v_mov_b32_e32 v0, s0
	ds_read_b32 v0, v0
	s_cbranch_vccnz .LBB0_1076
	s_add_u32 s0, s36, 0x1000
	s_addc_u32 s1, s37, 0
	s_add_u32 s2, s36, 0x1100
	s_addc_u32 s3, s37, 0
	s_add_u32 s6, s36, 0x1200
	s_addc_u32 s7, s37, 0
	s_add_u32 s8, s36, 0x1300
	s_addc_u32 s9, s37, 0
	s_mov_b32 s28, 1
	s_mov_b64 s[10:11], 0
	s_branch .LBB0_1066
